# start-up grid sync: dropped the per-workgroup L2 write-back before arrival (only block 0 wrote, and it writes through and releases itself)
# speedup vs baseline: 1.0028x; 1.0017x over previous
.LBB0_6:
	v_lshrrev_b32_e32 v2, 20, v0
	v_lshrrev_b32_e32 v0, 10, v0
	v_or_b32_e32 v0, v0, v2
	s_movk_i32 s2, 0x3ff
	v_and_or_b32 v0, v0, s2, v1
	v_cmp_eq_u32_e32 vcc, 0, v0
	s_waitcnt lgkmcnt(0)
	s_barrier
	s_and_saveexec_b64 s[2:3], vcc
	s_cbranch_execz .LBB0_16

	s_load_dwordx2 s[4:5], s[4:5], 0x58
	v_mov_b32_e32 v3, 0
	s_mov_b64 s[6:7], exec
	v_mbcnt_lo_u32_b32 v2, s6, 0
	v_mbcnt_hi_u32_b32 v2, s7, v2
	s_waitcnt lgkmcnt(0)
	global_load_dword v0, v3, s[4:5] offset:40
	v_cmp_eq_u32_e32 vcc, 0, v2
	s_and_saveexec_b64 s[8:9], vcc
	s_cbranch_execz .LBB0_9
	s_bcnt1_i32_b64 s6, s[6:7]
	v_mov_b32_e32 v4, s6
	global_atomic_add v4, v3, v4, s[4:5] offset:32 sc0
